# attention: V^T LDS tile re-laid out (144-byte rows, keys permuted per 16-key group) so each PV fragment is one ds_read_b128 instead of ds_read2_b64
# speedup vs baseline: 1.0238x; 1.0093x over previous
; __device__ __forceinline__ void unit(LAS unsigned char* lds, const bf16* __restrict__ Q, const bf16* __restrict__ Kn, const bf16* __restrict__ Kr, const bf16* __restrict__ Vt, bf16* __restrict__ O,
;                                      int tokbase, int S, int h, int qb, const int tid) {
;     const int lane = tid & 63, r32 = lane & 31, hi = lane >> 5, wid = __builtin_amdgcn_readfirstlane(tid >> 6);
;     const int NT = S / 64;
;     const int qrow = tokbase + qb * 256 + wid * 32 + r32;
;     bf16x8 qf[6];
; #pragma unroll
;     for (int d0 = 0; d0 < 6; ++d0) qf[d0] = *(const bf16x8*)(Q + (size_t)qrow * 1536 + h * 96 + d0 * 16 + hi * 8);
;     const int kkey = tid >> 3, kch = tid & 7;
;     const int rkey = (tid & 255) >> 2, rch = tid & 3;
;     const int vd = tid >> 3, vch = tid & 7;
;     const bf16* kp = Kn + (size_t)(tokbase + kkey) * 1024 + h * 64 + kch * 8;
;     const bf16* rp = Kr + (size_t)(tokbase + rkey) * 32 + rch * 8;
;     const bf16* vp = Vt + (size_t)(h * 64 + vd) * MH + tokbase + vch * 8;
;     u32x4 kreg, rreg = {0, 0, 0, 0}, vreg;
;     kreg = *(const u32x4*)kp; if (tid < 256) rreg = *(const u32x4*)rp; vreg = *(const u32x4*)vp;
.LBB0_712:
	s_andn2_b64 vcc, exec, s[6:7]
	s_cbranch_vccnz .LBB0_746
	v_readlane_b32 s8, v255, 13
	s_cmp_lt_i32 s8, 3
	s_mov_b64 s[6:7], -1
	s_cbranch_scc1 .LBB0_744
	s_cmp_eq_u32 s8, 3
	s_cbranch_scc0 .LBB0_743
	s_lshr_b32 s17, s18, 8
	s_and_b64 s[6:7], s[10:11], exec
	s_cselect_b32 s6, 7, 5
	s_abs_i32 s7, s3
	v_cvt_f32_u32_e32 v0, s7
	s_lshl_b32 s19, s17, s6
	s_sub_i32 s6, 0, s7
	s_add_i32 s8, s19, s3
	v_rcp_iflag_f32_e32 v0, v0
	s_add_i32 s8, s8, -1
	s_xor_b32 s9, s8, s3
	s_abs_i32 s8, s8
	v_mul_f32_e32 v0, 0x4f7ffffe, v0
	v_cvt_u32_f32_e32 v0, v0
	s_ashr_i32 s9, s9, 31
	v_readfirstlane_b32 s12, v0
	s_mul_i32 s6, s6, s12
	s_mul_hi_u32 s6, s12, s6
	s_add_i32 s12, s12, s6
	s_mul_hi_u32 s6, s8, s12
	s_mul_i32 s12, s6, s7
	s_sub_i32 s8, s8, s12
	s_add_i32 s13, s6, 1
	s_sub_i32 s12, s8, s7
	s_cmp_ge_u32 s8, s7
	s_cselect_b32 s6, s13, s6
	s_cselect_b32 s8, s12, s8
	s_add_i32 s12, s6, 1
	s_cmp_ge_u32 s8, s7
	s_cselect_b32 s6, s12, s6
	s_xor_b32 s6, s6, s9
	s_sub_i32 s22, s6, s9
	s_cmp_lt_i32 s22, 1
	s_cbranch_scc1 .LBB0_743
	s_waitcnt lgkmcnt(0)
	s_add_u32 s8, s50, 0x7e00000
	s_addc_u32 s9, s51, 0
	s_add_u32 s12, s50, 0xae00000
	s_addc_u32 s13, s51, 0
	s_add_u32 s14, s50, 0xce00000
	s_addc_u32 s15, s51, 0
	s_waitcnt vmcnt(0)
	v_lshlrev_b32_e32 v2, 4, v239
	s_add_u32 s23, s50, 0x3c00000
	v_ashrrev_i32_e32 v137, 3, v239
	v_bfe_u32 v143, v239, 2, 6
	v_and_b32_e32 v138, 48, v2
	v_mov_b32_e32 v139, v1
	s_movk_i32 s20, 0xd0
	s_addc_u32 s29, s51, 0
	v_lshl_add_u64 v[2:3], s[50:51], 0, v[138:139]
	v_mul_lo_u32 v139, v137, s20
	v_mad_u32_u24 v7, v143, s20, 0
	s_movk_i32 s20, 0x88
	s_and_b64 s[6:7], s[10:11], exec
	v_and_b32_e32 v4, 7, v239
	v_add_u32_e32 v142, 0, v139
	v_mul_lo_u32 v167, v137, s20
	s_movk_i32 s20, 0xffb8
	s_cselect_b32 s30, 11, 13
	v_lshlrev_b32_e32 v136, 3, v4
	v_lshlrev_b32_e32 v144, 4, v4
	v_mad_u64_u32 v[4:5], s[20:21], v137, s20, v[142:143]
	s_abs_i32 s31, s17
	v_cvt_f32_u32_e32 v5, s31
	s_sub_i32 s20, 0, s31
	v_lshrrev_b32_e32 v0, 5, v180
	v_lshlrev_b32_e32 v134, 3, v0
	v_rcp_iflag_f32_e32 v5, v5
	s_mov_b64 s[6:7], 0x7c00000
	v_lshlrev_b32_e32 v169, 4, v0
	v_lshrrev_b32_e32 v0, 3, v180
	v_mul_f32_e32 v5, 0x4f7ffffe, v5
	v_cvt_u32_f32_e32 v5, v5
	v_mov_b32_e32 v145, v1
	v_lshl_add_u64 v[140:141], v[2:3], 0, s[6:7]
	v_mul_u32_u24_e32 v172, 0x90, v0
	v_readfirstlane_b32 s21, v5
	s_mul_i32 s20, s20, s21
	s_mul_hi_u32 s20, s21, s20
	s_add_i32 s44, s21, s20
	s_mov_b64 s[20:21], 0x7c01000
	v_lshlrev_b32_e32 v0, 10, v0
	v_lshl_add_u64 v[146:147], v[2:3], 0, s[20:21]
	v_lshl_add_u64 v[2:3], s[50:51], 0, v[144:145]
	s_mov_b64 s[20:21], 0xce00080
	v_and_b32_e32 v135, 31, v239
	s_movk_i32 s6, 0x100
	v_or_b32_e32 v6, 0x2000, v0
	v_or_b32_e32 v8, 0x4000, v0
	v_or_b32_e32 v10, 0x6000, v0
	v_lshl_add_u64 v[148:149], v[2:3], 0, s[20:21]
	s_mov_b64 s[20:21], 0xae20000
	s_mul_i32 s5, s22, s5
	s_lshr_b32 s18, s18, 6
	v_cmp_gt_i32_e64 s[6:7], s6, v239
	v_mul_u32_u24_e32 v166, 0xd0, v143
	v_mul_u32_u24_e32 v168, 0xd0, v135
	v_mul_u32_u24_e32 v170, 0x90, v135
	v_mul_u32_u24_e32 v171, 0x90, v135
	s_ashr_i32 s34, s17, 31
	s_mov_b32 s39, 0
	v_lshl_add_u64 v[150:151], v[2:3], 0, s[20:21]
	v_add_u32_e32 v145, v7, v138
	v_mul_u32_u24_e32 v173, 0x90, v137
	v_and_b32_e32 v4, 7, v239
	v_lshrrev_b32_e32 v5, 1, v4
	v_lshl_add_u32 v173, v5, 5, v173
	v_and_b32_e32 v4, 1, v4
	v_lshl_add_u32 v173, v4, 3, v173
	v_add_u32_e32 v173, s86, v173
	v_lshlrev_b32_e32 v152, 1, v0
	v_lshlrev_b32_e32 v154, 1, v6
	v_lshlrev_b32_e32 v156, 1, v8
	v_lshlrev_b32_e32 v158, 1, v10
	s_branch .LBB0_720

; #define LAS __attribute__((address_space(3)))
; __device__ __forceinline__ void unit(LAS unsigned char* lds, const bf16* __restrict__ Q, const bf16* __restrict__ Kn, const bf16* __restrict__ Kr, const bf16* __restrict__ Vt, bf16* __restrict__ O,
;                                      int tokbase, int S, int h, int qb, const int tid) {
;     ...
;         {
;             bf16x8 vfa[2][2], vfb[2][2];
; #pragma unroll
;             for (int kt = 0; kt < 2; ++kt)
; #pragma unroll
;                 for (int s = 0; s < 2; ++s) {
;                     const int kcol = (kt * 32 + 16 * s + 4 * hi) * 2;
;                     const u32x2 a0 = *(const LAS u32x2*)(vb + r32 * VSTR + kcol), a1 = *(const LAS u32x2*)(vb + r32 * VSTR + kcol + 16);
;                     const u32x2 b0 = *(const LAS u32x2*)(vb + (32 + r32) * VSTR + kcol), b1 = *(const LAS u32x2*)(vb + (32 + r32) * VSTR + kcol + 16);
;                     vfa[kt][s] = __builtin_bit_cast(bf16x8, (u32x4){a0.x, a0.y, a1.x, a1.y});
;                     vfb[kt][s] = __builtin_bit_cast(bf16x8, (u32x4){b0.x, b0.y, b1.x, b1.y});
;                 }
;             __builtin_amdgcn_sched_barrier(0);
; #pragma unroll
;             for (int kt = 0; kt < 2; ++kt)
; #pragma unroll
;                 for (int s = 0; s < 2; ++s) {
;                     o0 = __builtin_amdgcn_mfma_f32_32x32x16_bf16(vfa[kt][s], pb[kt][s], o0, 0, 0, 0);
;                     o1 = __builtin_amdgcn_mfma_f32_32x32x16_bf16(vfb[kt][s], pb[kt][s], o1, 0, 0, 0);
;                 }
;         }
;         if (t + 1 < NT) ATT_WRITE((t + 1) & 1);
;         __syncthreads();
;     }
;     ...
;     l_run += __shfl_xor(l_run, 32);
;     const float inv = 1.0f / l_run;
;     LAS unsigned char* stg = lds + OST_OFF + wid * OST_WAVE;
; #pragma unroll
;     for (int r = 0; r < 16; ++r) { const int d = crow(r, hi);
;         *(LAS bf16*)(stg + r32 * 144 + d * 2) = f2bf(o0[r] * inv);
;         *(LAS bf16*)(stg + r32 * 144 + (32 + d) * 2) = f2bf(o1[r] * inv); }
;     asm volatile("s_waitcnt lgkmcnt(0)" ::: "memory");
;     bf16* Ow = O + (size_t)(tokbase + qb * 256 + wid * 32) * 1024 + h * 64;
; #pragma unroll
;     for (int i = 0; i < 4; ++i) { const int row = i * 8 + (lane >> 3), ch = lane & 7; const u32x4 v = *(const LAS u32x4*)(stg + row * 144 + ch * 16); *(u32x4*)(Ow + (size_t)row * 1024 + ch * 8) = v; }
.LBB0_718:
	v_add3_u32 v34, s37, v170, v169
	v_cvt_pk_bf16_f32 v46, v74, v75
	v_cvt_pk_bf16_f32 v48, v78, v79
	v_cvt_pk_bf16_f32 v38, v66, v67
	v_cvt_pk_bf16_f32 v39, v68, v69
	v_cvt_pk_bf16_f32 v40, v70, v71
	v_cvt_pk_bf16_f32 v41, v72, v73
	v_cvt_pk_bf16_f32 v47, v76, v77
	v_cvt_pk_bf16_f32 v49, v80, v81
	ds_read_b128 v[50:53], v34 offset:13312
	ds_read_b128 v[54:57], v34 offset:13344
	ds_read_b128 v[58:61], v34 offset:17920
	ds_read_b128 v[62:65], v34 offset:17952
	ds_read_b128 v[66:69], v34 offset:13376
	ds_read_b128 v[70:73], v34 offset:17984
	ds_read_b128 v[74:77], v34 offset:13408
	ds_read_b128 v[78:81], v34 offset:18016
	v_cvt_pk_bf16_f32 v34, v82, v83
	v_cvt_pk_bf16_f32 v35, v84, v85
	v_cvt_pk_bf16_f32 v36, v86, v87
	v_cvt_pk_bf16_f32 v37, v88, v89
	v_cvt_pk_bf16_f32 v42, v90, v91
	v_cvt_pk_bf16_f32 v43, v92, v93
	v_cvt_pk_bf16_f32 v44, v94, v95
	v_cvt_pk_bf16_f32 v45, v96, v97
	s_waitcnt lgkmcnt(7)
	v_mfma_f32_32x32x16_bf16 v[2:17], v[50:53], v[34:37], v[2:17]
	s_mulk_i32 s21, 0x1200
	s_waitcnt lgkmcnt(0)
	s_barrier
	v_mov_b32_e32 v157, v1
	v_mov_b32_e32 v159, v1
	v_mfma_f32_32x32x16_bf16 v[18:33], v[58:61], v[34:37], v[18:33]
	v_add_f32_e32 v34, v153, v98
	ds_bpermute_b32 v35, v155, v34
	v_mov_b32_e32 v153, v1
	v_mov_b32_e32 v155, v1
	s_waitcnt lgkmcnt(0)
	v_add_f32_e32 v34, v34, v35
	v_mfma_f32_32x32x16_bf16 v[2:17], v[54:57], v[42:45], v[2:17]
	v_div_scale_f32 v35, s[26:27], v34, v34, 1.0
	v_rcp_f32_e32 v36, v35
	s_add_i32 s26, s21, 0
	s_ashr_i32 s21, s20, 31
	s_lshl_b64 s[20:21], s[20:21], 11
	v_fma_f32 v37, -v35, v36, 1.0
	v_mfma_f32_32x32x16_bf16 v[18:33], v[62:65], v[42:45], v[18:33]
	v_fmac_f32_e32 v36, v37, v36
	v_div_scale_f32 v37, vcc, 1.0, v34, 1.0
	s_add_u32 s27, s23, s20
	s_addc_u32 s36, s29, s21
	s_lshl_b64 s[20:21], s[24:25], 1
	s_add_u32 s20, s27, s20
	v_mfma_f32_32x32x16_bf16 v[2:17], v[66:69], v[38:41], v[2:17]
	s_addc_u32 s21, s36, s21
	s_add_i32 s39, s39, 1
	s_cmp_eq_u32 s39, s22
	v_mfma_f32_32x32x16_bf16 v[18:33], v[70:73], v[38:41], v[18:33]
	v_mul_f32_e32 v38, v37, v36
	v_fma_f32 v39, -v35, v38, v37
	v_fmac_f32_e32 v38, v39, v36
	v_fma_f32 v35, -v35, v38, v37
	v_div_fmas_f32 v35, v35, v36, v38
	v_div_fixup_f32 v34, v35, v34, 1.0
	v_add3_u32 v35, s26, v171, v134
	v_mfma_f32_32x32x16_bf16 v[2:17], v[74:77], v[46:49], v[2:17]
	v_mfma_f32_32x32x16_bf16 v[18:33], v[78:81], v[46:49], v[18:33]
	s_nop 10
	v_mul_f32_e32 v36, v3, v34
	v_mul_f32_e32 v3, v4, v34
	v_mul_f32_e32 v5, v5, v34
	v_cvt_pk_bf16_f32 v3, v3, v5
	v_mul_f32_e32 v2, v2, v34
	v_mul_f32_e32 v6, v6, v34
	v_mul_f32_e32 v9, v9, v34
	v_mul_f32_e32 v18, v18, v34
	v_mul_f32_e32 v19, v19, v34
	v_mul_f32_e32 v4, v20, v34
	v_mul_f32_e32 v5, v21, v34
	v_cvt_pk_bf16_f32 v5, v4, v5
	v_cvt_pk_bf16_f32 v4, v18, v19
	v_mul_f32_e32 v19, v7, v34
	v_mul_f32_e32 v7, v8, v34
	v_cvt_pk_bf16_f32 v2, v2, v36
	v_cvt_pk_bf16_f32 v7, v7, v9
	v_cvt_pk_bf16_f32 v6, v6, v19
	v_add_u32_e32 v9, 0xb000, v35
	v_mul_f32_e32 v18, v22, v34
	v_mul_f32_e32 v20, v23, v34
	v_mul_f32_e32 v8, v24, v34
	ds_write2_b64 v9, v[2:3], v[6:7] offset1:2
	v_mul_f32_e32 v2, v25, v34
	v_cvt_pk_bf16_f32 v3, v8, v2
	v_cvt_pk_bf16_f32 v2, v18, v20
	ds_write2_b64 v9, v[4:5], v[2:3] offset0:8 offset1:10
	v_mul_f32_e32 v2, v10, v34
	v_mul_f32_e32 v5, v11, v34
	v_mul_f32_e32 v4, v26, v34
	v_mul_f32_e32 v6, v27, v34
	v_mul_f32_e32 v7, v28, v34
	v_cvt_pk_bf16_f32 v2, v2, v5
	v_mul_f32_e32 v5, v29, v34
	v_mul_f32_e32 v3, v12, v34
	v_mul_f32_e32 v8, v13, v34
	v_cvt_pk_bf16_f32 v5, v7, v5
	v_cvt_pk_bf16_f32 v4, v4, v6
	v_mul_f32_e32 v6, v14, v34
	v_mul_f32_e32 v10, v15, v34
	v_mul_f32_e32 v7, v16, v34
	v_mul_f32_e32 v13, v17, v34
	v_cvt_pk_bf16_f32 v3, v3, v8
	v_cvt_pk_bf16_f32 v7, v7, v13
	v_cvt_pk_bf16_f32 v6, v6, v10
	v_mul_f32_e32 v8, v30, v34
	v_mul_f32_e32 v11, v31, v34
	v_mul_f32_e32 v12, v32, v34
	ds_write2_b64 v9, v[2:3], v[6:7] offset0:4 offset1:6
	v_mul_f32_e32 v2, v33, v34
	v_cvt_pk_bf16_f32 v3, v12, v2
	v_cvt_pk_bf16_f32 v2, v8, v11
	ds_write2_b64 v9, v[4:5], v[2:3] offset0:12 offset1:14
	s_waitcnt lgkmcnt(0)
	v_add3_u32 v14, s26, v144, v172
	ds_read_b128 v[2:5], v14 offset:45056
	ds_read_b128 v[6:9], v14 offset:46208
	v_lshl_add_u64 v[10:11], s[20:21], 0, v[0:1]
	v_lshl_add_u64 v[12:13], v[10:11], 0, v[152:153]
	s_cselect_b64 s[20:21], -1, 0
	s_waitcnt lgkmcnt(1)
	global_store_dwordx4 v[12:13], v[2:5], off
	v_lshl_add_u64 v[12:13], v[10:11], 0, v[154:155]
	ds_read_b128 v[2:5], v14 offset:47360
	s_waitcnt lgkmcnt(1)
	global_store_dwordx4 v[12:13], v[6:9], off
	ds_read_b128 v[6:9], v14 offset:48512
	v_lshl_add_u64 v[12:13], v[10:11], 0, v[156:157]
	s_waitcnt lgkmcnt(1)
	global_store_dwordx4 v[12:13], v[2:5], off
	s_nop 1
	v_lshl_add_u64 v[2:3], v[10:11], 0, v[158:159]
	s_waitcnt lgkmcnt(0)
	global_store_dwordx4 v[2:3], v[6:9], off
	s_barrier

; __device__ __forceinline__ void unit(LAS unsigned char* lds, const bf16* __restrict__ Q, const bf16* __restrict__ Kn, const bf16* __restrict__ Kr, const bf16* __restrict__ Vt, bf16* __restrict__ O,
;                                      int tokbase, int S, int h, int qb, const int tid) {
;     ...
;     kreg = *(const u32x4*)kp; if (tid < 256) rreg = *(const u32x4*)rp; vreg = *(const u32x4*)vp;
;     ...
;     ATT_WRITE(0);
;     __syncthreads();
;     float mref = 0.f, l_run = 0.f;
;     f32x16 o0 = {}, o1 = {};
;     ...
;         if (t + 1 < NT) ATT_WRITE((t + 1) & 1);
;         __syncthreads();
.LBB0_723:
	s_or_b64 exec, exec, s[36:37]
	v_add_u32_e32 v6, s24, v137
	v_ashrrev_i32_e32 v7, 31, v6
	v_lshlrev_b64 v[12:13], 15, v[6:7]
	v_lshl_add_u64 v[6:7], s[14:15], 0, v[12:13]
	s_ashr_i32 s27, s26, 31
	v_lshl_add_u64 v[6:7], s[26:27], 1, v[6:7]
	v_lshl_add_u64 v[6:7], v[6:7], 0, v[0:1]
	global_load_dwordx4 v[6:9], v[6:7], off
	v_add_u32_e32 v14, v142, v144
	s_waitcnt vmcnt(1)
	ds_write_b128 v14, v[2:5]
	s_and_saveexec_b64 s[36:37], s[6:7]
	ds_write_b128 v145, v[122:125] offset:128
	s_or_b64 exec, exec, s[36:37]
	v_add_u32_e32 v2, s26, v143
	v_ashrrev_i32_e32 v3, 31, v2
	v_lshlrev_b64 v[2:3], 6, v[2:3]
	v_lshl_add_u64 v[160:161], v[146:147], 0, v[2:3]
	v_lshl_add_u64 v[2:3], s[26:27], 1, v[12:13]
	v_lshl_add_u64 v[162:163], v[148:149], 0, v[2:3]
	v_lshl_add_u64 v[2:3], s[24:25], 1, v[10:11]
	v_mov_b32_e32 v16, v1
	v_mov_b32_e32 v17, v1
	s_waitcnt vmcnt(0)
	ds_write2_b64 v173, v[6:7], v[8:9] offset1:2
	v_lshl_add_u64 v[164:165], v[150:151], 0, v[2:3]
	v_mov_b32_e32 v2, v1
	v_mov_b32_e32 v3, v1
	v_mov_b32_e32 v4, v1
	v_mov_b32_e32 v5, v1
	v_mov_b32_e32 v6, v1
	v_mov_b32_e32 v7, v1
	v_mov_b32_e32 v8, v1
	v_mov_b32_e32 v9, v1
	v_mov_b32_e32 v10, v1
	v_mov_b32_e32 v11, v1
	v_mov_b32_e32 v12, v1
	v_mov_b32_e32 v13, v1
	v_mov_b32_e32 v14, v1
	v_mov_b32_e32 v15, v1
	v_mov_b64_e32 v[32:33], v[16:17]
	s_mov_b32 s36, 1
	v_mov_b32_e32 v153, 0
	v_mov_b32_e32 v157, 0
	v_mov_b64_e32 v[30:31], v[14:15]
	v_mov_b64_e32 v[28:29], v[12:13]
	v_mov_b64_e32 v[26:27], v[10:11]
	v_mov_b64_e32 v[24:25], v[8:9]
	v_mov_b64_e32 v[22:23], v[6:7]
	v_mov_b64_e32 v[20:21], v[4:5]
	v_mov_b64_e32 v[18:19], v[2:3]
	s_waitcnt lgkmcnt(0)
	s_barrier
	s_branch .LBB0_727
.LBB0_726:
	s_or_b64 exec, exec, s[26:27]
	s_mov_b64 s[26:27], 0x1000
	v_add_u32_e32 v34, s37, v173
	s_add_i32 s36, s36, 1
	v_lshl_add_u64 v[160:161], v[160:161], 0, s[26:27]
	s_mov_b64 s[26:27], 0x20000
	v_add_f32_e32 v153, v153, v159
	v_lshl_add_u64 v[162:163], v[162:163], 0, s[40:41]
	s_cmp_eq_u32 s18, s36
	v_lshl_add_u64 v[164:165], v[164:165], 0, s[26:27]
	s_waitcnt vmcnt(0)
	ds_write2_b64 v34, v[126:127], v[128:129] offset1:2
	s_waitcnt lgkmcnt(0)
	s_barrier
	s_cbranch_scc1 .LBB0_737

; #define LAS __attribute__((address_space(3)))
; #define MAX3(a, b, c) ({ float r_; asm("v_max3_f32 %0, %1, %2, %3" : "=v"(r_) : "v"(a), "v"(b), "v"(c)); r_; })
; __device__ __forceinline__ void unit(LAS unsigned char* lds, const bf16* __restrict__ Q, const bf16* __restrict__ Kn, const bf16* __restrict__ Kr, const bf16* __restrict__ Vt, bf16* __restrict__ O,
;                                      int tokbase, int S, int h, int qb, const int tid) {
;     ...
;         const LAS unsigned char* kb = lds + (t & 1) * BUFB;
;         const LAS unsigned char* vb = kb + KBYTES;
;         f32x16 p0 = {}, p1 = {};
;         {
;             bf16x8 kf0[6], kf1[6];
; #pragma unroll
;             for (int d0 = 0; d0 < 6; ++d0) { kf0[d0] = *(const LAS bf16x8*)(kb + r32 * KSTR + d0 * 32 + hi * 16); kf1[d0] = *(const LAS bf16x8*)(kb + (32 + r32) * KSTR + d0 * 32 + hi * 16); }
;             __builtin_amdgcn_sched_barrier(0);
; #pragma unroll
;             for (int d0 = 0; d0 < 6; ++d0) { p0 = __builtin_amdgcn_mfma_f32_32x32x16_bf16(kf0[d0], qf[d0], p0, 0, 0, 0); p1 = __builtin_amdgcn_mfma_f32_32x32x16_bf16(kf1[d0], qf[d0], p1, 0, 0, 0); }
;         }
;         float mx = MAX3(p0[0], p0[1], p0[2]);
;         mx = MAX3(mx, p0[3], p0[4]); mx = MAX3(mx, p0[5], p0[6]); mx = MAX3(mx, p0[7], p0[8]); mx = MAX3(mx, p0[9], p0[10]); mx = MAX3(mx, p0[11], p0[12]);
;         mx = MAX3(mx, p0[13], p0[14]); mx = MAX3(mx, p0[15], p1[0]); mx = MAX3(mx, p1[1], p1[2]); mx = MAX3(mx, p1[3], p1[4]); mx = MAX3(mx, p1[5], p1[6]);
;         mx = MAX3(mx, p1[7], p1[8]); mx = MAX3(mx, p1[9], p1[10]); mx = MAX3(mx, p1[11], p1[12]); mx = MAX3(mx, p1[13], p1[14]); mx = MAX3(mx, p1[15], p1[15]);
;         { const float mo = __shfl_xor(mx, 32); mx = MAX3(mx, mo, mo); }
;         if (__any(mx - mref > 8.0f)) {
;             const float dl = fmaxf(mx - mref, 0.f);
;             mref += dl;
;             const float alpha = __builtin_amdgcn_exp2f(-dl);
;             l_run *= alpha;
; #pragma unroll
;             for (int r = 0; r < 16; ++r) { o0[r] *= alpha; o1[r] *= alpha; }
;         }
.LBB0_729:
	s_or_b64 exec, exec, s[26:27]
	global_load_dwordx4 v[126:129], v[162:163], off
	s_and_b32 s37, 1, s36
	s_cselect_b32 s26, 0, 0x5800
	s_add_i32 s45, s26, 0
	v_add3_u32 v42, s45, v168, v169
	ds_read_b128 v[34:37], v42
	ds_read_b128 v[66:69], v42 offset:32
	ds_read_b128 v[38:41], v42 offset:6656
	ds_read_b128 v[70:73], v42 offset:6688
	ds_read_b128 v[74:77], v42 offset:64
	ds_read_b128 v[78:81], v42 offset:96
	ds_read_b128 v[82:85], v42 offset:6720
	ds_read_b128 v[86:89], v42 offset:6752
	ds_read_b128 v[90:93], v42 offset:128
	ds_read_b128 v[94:97], v42 offset:160
	ds_read_b128 v[174:177], v42 offset:6784
	ds_read_b128 v[182:185], v42 offset:6816
	s_waitcnt lgkmcnt(11)
	v_mfma_f32_32x32x16_bf16 v[50:65], v[34:37], v[118:121], 0
	s_waitcnt lgkmcnt(9)
	v_mfma_f32_32x32x16_bf16 v[34:49], v[38:41], v[118:121], 0
	v_mfma_f32_32x32x16_bf16 v[50:65], v[66:69], v[114:117], v[50:65]
	v_and_b32_e32 v68, 64, v238
	v_xor_b32_e32 v67, 32, v238
	v_add_u32_e32 v68, 64, v68
	v_cmp_lt_i32_e32 vcc, v67, v68
	s_nop 1
	v_cndmask_b32_e32 v67, v238, v67, vcc
	s_waitcnt lgkmcnt(8)
	v_mfma_f32_32x32x16_bf16 v[34:49], v[70:73], v[114:117], v[34:49]
	v_lshlrev_b32_e32 v155, 2, v67
	s_waitcnt lgkmcnt(7)
	v_mfma_f32_32x32x16_bf16 v[50:65], v[74:77], v[110:113], v[50:65]
	s_waitcnt lgkmcnt(5)
	v_mfma_f32_32x32x16_bf16 v[34:49], v[82:85], v[110:113], v[34:49]
	v_mfma_f32_32x32x16_bf16 v[50:65], v[78:81], v[106:109], v[50:65]
	s_waitcnt lgkmcnt(4)
	v_mfma_f32_32x32x16_bf16 v[34:49], v[86:89], v[106:109], v[34:49]
	s_waitcnt lgkmcnt(3)
	v_mfma_f32_32x32x16_bf16 v[50:65], v[90:93], v[102:105], v[50:65]
	s_waitcnt lgkmcnt(1)
	v_mfma_f32_32x32x16_bf16 v[34:49], v[174:177], v[102:105], v[34:49]
	v_mfma_f32_32x32x16_bf16 v[50:65], v[94:97], v[98:101], v[50:65]
	v_max3_f32 v66, v50, v51, v52
	s_nop 0
	v_max3_f32 v66, v66, v53, v54
	s_nop 0
	v_max3_f32 v66, v66, v55, v56
	s_nop 0
	v_max3_f32 v66, v66, v57, v58
	s_waitcnt lgkmcnt(0)
	v_mfma_f32_32x32x16_bf16 v[34:49], v[182:185], v[98:101], v[34:49]
	v_max3_f32 v66, v66, v59, v60
	s_nop 0
	v_max3_f32 v66, v66, v61, v62
	s_nop 0
	v_max3_f32 v66, v66, v63, v64
	s_nop 0
	v_max3_f32 v66, v66, v65, v34
	s_nop 0
	v_max3_f32 v66, v66, v35, v36
	s_nop 0
	v_max3_f32 v66, v66, v37, v38
	s_nop 0
	v_max3_f32 v66, v66, v39, v40
	s_nop 0
	v_max3_f32 v66, v66, v41, v42
	s_nop 0
	v_max3_f32 v66, v66, v43, v44
	s_nop 0
	v_max3_f32 v66, v66, v45, v46
	s_nop 0
	v_max3_f32 v66, v66, v47, v48
	s_nop 0
	v_max3_f32 v66, v66, v49, v49
	ds_bpermute_b32 v67, v155, v66
	s_waitcnt lgkmcnt(0)
	v_max3_f32 v66, v66, v67, v67
	s_nop 0
	v_sub_f32_e32 v66, v66, v157
	v_cmp_lt_f32_e32 vcc, s87, v66
	s_cbranch_vccz .LBB0_731
	v_max_f32_e32 v66, v66, v66
	v_max_f32_e32 v67, 0, v66
	v_exp_f32_e64 v66, -v67
	v_add_f32_e32 v157, v157, v67
	v_pk_mul_f32 v[16:17], v[16:17], v[66:67] op_sel_hi:[1,0]
	v_pk_mul_f32 v[14:15], v[14:15], v[66:67] op_sel_hi:[1,0]
	v_pk_mul_f32 v[12:13], v[12:13], v[66:67] op_sel_hi:[1,0]
	v_pk_mul_f32 v[10:11], v[10:11], v[66:67] op_sel_hi:[1,0]
	v_pk_mul_f32 v[8:9], v[8:9], v[66:67] op_sel_hi:[1,0]
	v_pk_mul_f32 v[6:7], v[6:7], v[66:67] op_sel_hi:[1,0]
	v_pk_mul_f32 v[4:5], v[4:5], v[66:67] op_sel_hi:[1,0]
	v_pk_mul_f32 v[2:3], v[2:3], v[66:67] op_sel_hi:[1,0]
	v_pk_mul_f32 v[32:33], v[32:33], v[66:67] op_sel_hi:[1,0]
	v_pk_mul_f32 v[30:31], v[30:31], v[66:67] op_sel_hi:[1,0]
	v_pk_mul_f32 v[28:29], v[28:29], v[66:67] op_sel_hi:[1,0]
	v_pk_mul_f32 v[26:27], v[26:27], v[66:67] op_sel_hi:[1,0]
	v_pk_mul_f32 v[24:25], v[24:25], v[66:67] op_sel_hi:[1,0]
	v_pk_mul_f32 v[22:23], v[22:23], v[66:67] op_sel_hi:[1,0]
	v_pk_mul_f32 v[20:21], v[20:21], v[66:67] op_sel_hi:[1,0]
	v_pk_mul_f32 v[18:19], v[18:19], v[66:67] op_sel_hi:[1,0]
	v_mul_f32_e32 v153, v153, v66

; #define LAS __attribute__((address_space(3)))
; __device__ __forceinline__ void unit(LAS unsigned char* lds, const bf16* __restrict__ Q, const bf16* __restrict__ Kn, const bf16* __restrict__ Kr, const bf16* __restrict__ Vt, bf16* __restrict__ O,
;                                      int tokbase, int S, int h, int qb, const int tid) {
;     ...
;         {
;             bf16x8 vfa[2][2], vfb[2][2];
; #pragma unroll
;             for (int kt = 0; kt < 2; ++kt)
; #pragma unroll
;                 for (int s = 0; s < 2; ++s) {
;                     const int kcol = (kt * 32 + 16 * s + 4 * hi) * 2;
;                     const u32x2 a0 = *(const LAS u32x2*)(vb + r32 * VSTR + kcol), a1 = *(const LAS u32x2*)(vb + r32 * VSTR + kcol + 16);
;                     const u32x2 b0 = *(const LAS u32x2*)(vb + (32 + r32) * VSTR + kcol), b1 = *(const LAS u32x2*)(vb + (32 + r32) * VSTR + kcol + 16);
;                     vfa[kt][s] = __builtin_bit_cast(bf16x8, (u32x4){a0.x, a0.y, a1.x, a1.y});
;                     vfb[kt][s] = __builtin_bit_cast(bf16x8, (u32x4){b0.x, b0.y, b1.x, b1.y});
;                 }
;             __builtin_amdgcn_sched_barrier(0);
; #pragma unroll
;             for (int kt = 0; kt < 2; ++kt)
; #pragma unroll
;                 for (int s = 0; s < 2; ++s) {
;                     o0 = __builtin_amdgcn_mfma_f32_32x32x16_bf16(vfa[kt][s], pb[kt][s], o0, 0, 0, 0);
;                     o1 = __builtin_amdgcn_mfma_f32_32x32x16_bf16(vfb[kt][s], pb[kt][s], o1, 0, 0, 0);
;                 }
;         }
;         if (t + 1 < NT) ATT_WRITE((t + 1) & 1);
.LBB0_734:
	v_add3_u32 v34, s45, v170, v169
	v_cvt_pk_bf16_f32 v46, v74, v75
	v_cvt_pk_bf16_f32 v48, v78, v79
	v_cvt_pk_bf16_f32 v38, v66, v67
	v_cvt_pk_bf16_f32 v39, v68, v69
	v_cvt_pk_bf16_f32 v40, v70, v71
	v_cvt_pk_bf16_f32 v41, v72, v73
	v_cvt_pk_bf16_f32 v47, v76, v77
	v_cvt_pk_bf16_f32 v49, v80, v81
	ds_read_b128 v[50:53], v34 offset:13312
	ds_read_b128 v[54:57], v34 offset:13344
	ds_read_b128 v[58:61], v34 offset:17920
	ds_read_b128 v[62:65], v34 offset:17952
	ds_read_b128 v[66:69], v34 offset:13376
	ds_read_b128 v[70:73], v34 offset:17984
	ds_read_b128 v[74:77], v34 offset:13408
	ds_read_b128 v[78:81], v34 offset:18016
	v_cvt_pk_bf16_f32 v34, v82, v83
	v_cvt_pk_bf16_f32 v35, v84, v85
	v_cvt_pk_bf16_f32 v36, v86, v87
	v_cvt_pk_bf16_f32 v37, v88, v89
	v_cvt_pk_bf16_f32 v42, v90, v91
	v_cvt_pk_bf16_f32 v43, v92, v93
	v_cvt_pk_bf16_f32 v44, v94, v95
	v_cvt_pk_bf16_f32 v45, v96, v97
	s_waitcnt lgkmcnt(7)
	v_mfma_f32_32x32x16_bf16 v[2:17], v[50:53], v[34:37], v[2:17]
	s_cmp_eq_u32 s37, 1
	s_cselect_b32 s26, 0x5800, 0
	s_add_i32 s37, s26, 0
	s_waitcnt lgkmcnt(5)
	v_mfma_f32_32x32x16_bf16 v[18:33], v[58:61], v[34:37], v[18:33]
	v_add3_u32 v34, s37, v139, v144
	s_waitcnt vmcnt(1)
	ds_write_b128 v34, v[130:133]
	v_mfma_f32_32x32x16_bf16 v[2:17], v[54:57], v[42:45], v[2:17]
	s_waitcnt lgkmcnt(5)
	v_mfma_f32_32x32x16_bf16 v[18:33], v[62:65], v[42:45], v[18:33]
	s_waitcnt lgkmcnt(4)
	v_mfma_f32_32x32x16_bf16 v[2:17], v[66:69], v[38:41], v[2:17]
	s_waitcnt lgkmcnt(3)
	v_mfma_f32_32x32x16_bf16 v[18:33], v[70:73], v[38:41], v[18:33]
	s_waitcnt lgkmcnt(2)
	v_mfma_f32_32x32x16_bf16 v[2:17], v[74:77], v[46:49], v[2:17]
	s_waitcnt lgkmcnt(1)
	v_mfma_f32_32x32x16_bf16 v[18:33], v[78:81], v[46:49], v[18:33]
	s_and_saveexec_b64 s[26:27], s[6:7]
	s_cbranch_execz .LBB0_726
	v_add3_u32 v34, s37, v166, v138
	ds_write_b128 v34, v[122:125] offset:128
	s_branch .LBB0_726
